# grid barrier: the 16th workgroup of each XCD to arrive issues one early L2 writeback (buffer_wbl2 sc1, not waited) so the XCD leader's release flush has less to write; plus the early non-leader L1 inv
# speedup vs baseline: 1.0140x; 1.0017x over previous
; __device__ __forceinline__ unsigned xb_ld(unsigned* p)              { return __hip_atomic_load(p, __ATOMIC_RELAXED, __HIP_MEMORY_SCOPE_AGENT); }
; __device__ __forceinline__ unsigned xb_add(unsigned* p, unsigned v) { return __hip_atomic_fetch_add(p, v, __ATOMIC_RELAXED, __HIP_MEMORY_SCOPE_AGENT); }
; #define XB_SPIN(cond, bar) do { unsigned _sp = 0; while (cond) { __builtin_amdgcn_s_sleep(1); \
;     if ((++_sp & 255u) == 0u) { if (xb_ld(&(bar)[XB_TMO])) break; if (_sp > XB_SPIN_CAP) { atomicAdd(&(bar)[XB_TMO], 1u); break; } } } } while (0)
; __device__ __forceinline__ void xcd_barrier(const XcdBarrier& b, const bool t0) {
;     ...
;         const unsigned old = xb_add(&bar[XB_XSUB(b.x)], 1u);
;         const unsigned gen = old / nloc;
;         if (old + 1u == (gen + 1u) * nloc) {
;             __builtin_amdgcn_fence(__ATOMIC_RELEASE, "agent");
;             asm volatile("s_waitcnt vmcnt(0)" ::: "memory");
;             const unsigned og = xb_add(&bar[XB_TOP], 1u);
;             const unsigned tg = og / nx;
;             if (og + 1u == (tg + 1u) * nx) xb_add(&bar[XB_TOPGEN], 1u);
;             else XB_SPIN(xb_ld(&bar[XB_TOPGEN]) == tg, bar);
;             __builtin_amdgcn_fence(__ATOMIC_ACQUIRE, "agent");
;             xb_add(&bar[XB_XGEN(b.x)], 1u);
;             asm volatile("s_waitcnt vmcnt(0)" ::: "memory");
;         } else {
;             XB_SPIN(xb_ld(&bar[XB_XGEN(b.x)]) == gen, bar);
;             __builtin_amdgcn_fence(__ATOMIC_ACQUIRE, "agent");
.LBB0_391:
	s_or_b64 exec, exec, s[4:5]
	v_cvt_f32_u32_e32 v5, v3
	s_waitcnt vmcnt(0)
	v_readfirstlane_b32 s4, v4
	v_sub_u32_e32 v4, 0, v3
	v_rcp_iflag_f32_e32 v5, v5
	v_add_u32_e32 v6, s4, v0
	v_mul_f32_e32 v5, 0x4f7ffffe, v5
	v_cvt_u32_f32_e32 v5, v5
	v_mul_lo_u32 v0, v4, v5
	v_mul_hi_u32 v0, v5, v0
	v_add_u32_e32 v0, v5, v0
	v_mul_hi_u32 v0, v6, v0
	v_mul_lo_u32 v4, v0, v3
	v_sub_u32_e32 v4, v6, v4
	v_add_u32_e32 v5, 1, v0
	v_cmp_ge_u32_e32 vcc, v4, v3
	s_nop 1
	v_cndmask_b32_e32 v0, v0, v5, vcc
	v_sub_u32_e32 v5, v4, v3
	v_cndmask_b32_e32 v4, v4, v5, vcc
	v_add_u32_e32 v5, 1, v0
	v_cmp_ge_u32_e32 vcc, v4, v3
	v_add_u32_e32 v4, 1, v6
	s_nop 0
	v_cndmask_b32_e32 v0, v0, v5, vcc
	v_mul_lo_u32 v5, v3, v0
	v_add_u32_e32 v3, v5, v3
	v_cmp_ne_u32_e32 vcc, v4, v3
	s_and_saveexec_b64 s[4:5], vcc
	s_xor_b64 s[4:5], exec, s[4:5]
	s_cbranch_execz .LBB0_405
	v_readfirstlane_b32 s98, v6
	s_and_b32 s98, s98, 31
	s_cmp_eq_u32 s98, 15
	s_cbranch_scc0 .Lxb_nowb0
	buffer_wbl2 sc1
.Lxb_nowb0:
	buffer_inv sc1
	v_readlane_b32 s6, v253, 23
	v_readlane_b32 s7, v253, 24
	s_waitcnt lgkmcnt(0)
	s_nop 3
	global_load_dword v2, v1, s[6:7] sc1
	s_waitcnt vmcnt(0)
	v_cmp_eq_u32_e32 vcc, v2, v0
	s_and_saveexec_b64 s[6:7], vcc
	s_cbranch_execz .LBB0_404
	s_mov_b32 s12, 1
	s_mov_b64 s[8:9], 0
	s_branch .LBB0_395
